# attention prologues: drop compiler vmcnt ladder that waited on just-issued LDS-DMA tiles
# speedup vs baseline: 1.0023x; 1.0023x over previous
; #define LAS __attribute__((address_space(3)))
; #define MFMA32(a, b, c) __builtin_amdgcn_mfma_f32_32x32x16_bf16((a), (b), (c), 0, 0, 0)
; #define WAIT_BAR(N) asm volatile("s_waitcnt vmcnt(" #N ") lgkmcnt(0)\n\ts_barrier" ::: "memory")
; template <int NKD, int KSTRIDE> __device__ __forceinline__ void att_qk(const LAS unsigned char* kb, const bf16x8 (&qr)[NKD], f32x16& c0, f32x16& c1) {
;     f32x16 z;
; #pragma unroll
;     for (int r = 0; r < 16; ++r) z[r] = 0.f;
; #pragma unroll
;     for (int d0 = 0; d0 < NKD; ++d0) { const bf16x8 k0 = *(const LAS bf16x8*)(kb + d0 * 32), k1 = *(const LAS bf16x8*)(kb + 32 * KSTRIDE + d0 * 32);
;         c0 = MFMA32(k0, qr[d0], d0 == 0 ? z : c0); c1 = MFMA32(k1, qr[d0], d0 == 0 ? z : c1); }
; __device__ __forceinline__ void attn_mla_unit(LAS unsigned char* lds, const bf16_t* __restrict__ QM, const bf16_t* __restrict__ Kb, const bf16_t* __restrict__ KR, const bf16_t* __restrict__ VT, bf16_t* O,
;                                               int qrow0, int b, int h, int ntiles) {
;     ...
;     WAIT_BAR(3);
;     M_ISSUE();
;     att_qk<6, MK_STRIDE>(lds + koff, qr, pA0, pA1);
;     att_first(pA0, pA1, mhat);
;     WAIT_BAR(3);
.LBB0_750:
	s_movk_i32 s11, 0xd0
	v_mad_u32_u24 v193, v172, s11, v194
	v_add_u32_e32 v204, 0, v193
	ds_read_b128 v[0:3], v204
	ds_read_b128 v[32:35], v204 offset:32
	v_cmp_lt_i32_e32 vcc, v221, v220
	s_movk_i32 s4, 0x90
	v_mad_u32_u24 v163, v172, s4, v194
	s_waitcnt lgkmcnt(1)
	v_mfma_f32_32x32x16_bf16 v[16:31], v[0:3], v[116:119], 0
	ds_read_b128 v[0:3], v204 offset:6656
	ds_read_b128 v[36:39], v204 offset:6688
	s_cmp_lt_i32 s10, 4
	s_movk_i32 s4, 0x100
	s_cselect_b64 s[48:49], -1, 0
	s_cmp_gt_i32 s10, 3
	s_mov_b32 s11, 0
	v_add_u32_e32 v205, 0, v163
	s_waitcnt lgkmcnt(1)
	v_mfma_f32_32x32x16_bf16 v[0:15], v[0:3], v[116:119], 0
	s_mov_b32 s13, 3
	s_cselect_b64 s[52:53], -1, 0
	s_mov_b32 s10, 0
	s_nop 0
	v_mfma_f32_32x32x16_bf16 v[16:31], v[32:35], v[112:115], v[16:31]
	s_waitcnt lgkmcnt(0)
	v_mfma_f32_32x32x16_bf16 v[0:15], v[36:39], v[112:115], v[0:15]
	ds_read_b128 v[32:35], v204 offset:64
	ds_read_b128 v[36:39], v204 offset:96
	s_waitcnt lgkmcnt(1)
	v_mfma_f32_32x32x16_bf16 v[16:31], v[32:35], v[108:111], v[16:31]
	ds_read_b128 v[32:35], v204 offset:6720
	ds_read_b128 v[40:43], v204 offset:6752
	s_waitcnt lgkmcnt(1)
	v_mfma_f32_32x32x16_bf16 v[0:15], v[32:35], v[108:111], v[0:15]
	s_nop 0
	v_mfma_f32_32x32x16_bf16 v[16:31], v[36:39], v[104:107], v[16:31]
	ds_read_b128 v[32:35], v204 offset:128
	ds_read_b128 v[36:39], v204 offset:160
	s_waitcnt lgkmcnt(2)
	v_mfma_f32_32x32x16_bf16 v[0:15], v[40:43], v[104:107], v[0:15]
	s_waitcnt lgkmcnt(1)
	v_mfma_f32_32x32x16_bf16 v[16:31], v[32:35], v[100:103], v[16:31]
	ds_read_b128 v[32:35], v204 offset:6784
	ds_read_b128 v[40:43], v204 offset:6816
	s_waitcnt vmcnt(3) lgkmcnt(0)
	s_barrier
; #define WAIT_BAR(N) asm volatile("s_waitcnt vmcnt(" #N ") lgkmcnt(0)\n\ts_barrier" ::: "memory")
; __device__ __forceinline__ void att_first(f32x16& c0, f32x16& c1, float& mhat) {
;     float rm = fmaxf(c0[0], c1[0]);
; #pragma unroll
;     for (int r = 1; r < 16; ++r) rm = fmaxf(rm, fmaxf(c0[r], c1[r]));
;     rm = fmaxf(rm, __shfl_xor(rm, 32)); mhat = rm;
; #pragma unroll
;     for (int r = 0; r < 16; ++r) { c0[r] = __builtin_amdgcn_exp2f(c0[r] - mhat); c1[r] = __builtin_amdgcn_exp2f(c1[r] - mhat); }
; }
; __device__ __forceinline__ void attn_mla_unit(LAS unsigned char* lds, const bf16_t* __restrict__ QM, const bf16_t* __restrict__ Kb, const bf16_t* __restrict__ KR, const bf16_t* __restrict__ VT, bf16_t* O,
;                                               int qrow0, int b, int h, int ntiles) {
;     ...
;     f32x16 o[2];
; #pragma unroll
;     for (int k = 0; k < 2; ++k)
; #pragma unroll
;         for (int r = 0; r < 16; ++r) o[k][r] = 0.f;
;     float mhat = 0.f, lrun = 0.f, fsc = 1.f;
;     f32x16 pA0, pA1, pB0, pB1; bf16x8 pf[4], vf[8];
;     ...
;     att_qk<6, MK_STRIDE>(lds + koff, qr, pA0, pA1);
;     att_first(pA0, pA1, mhat);
;     WAIT_BAR(3);
	s_waitcnt lgkmcnt(1)
	v_mfma_f32_32x32x16_bf16 v[0:15], v[32:35], v[100:103], v[0:15]
	s_waitcnt lgkmcnt(0)
	v_mfma_f32_32x32x16_bf16 v[0:15], v[40:43], v[96:99], v[0:15]
	v_mfma_f32_32x32x16_bf16 v[16:31], v[36:39], v[96:99], v[16:31]
	s_nop 10
	v_max_f32_e32 v32, v1, v1
	v_max_f32_e32 v33, v17, v17
	v_max_f32_e32 v32, v33, v32
	v_max_f32_e32 v33, v2, v2
	v_max_f32_e32 v34, v18, v18
	v_max_f32_e32 v33, v34, v33
	v_max_f32_e32 v34, v3, v3
	v_max_f32_e32 v35, v19, v19
	v_max3_f32 v32, v16, v0, v32
	v_max_f32_e32 v34, v35, v34
	v_max3_f32 v32, v32, v33, v34
	v_max_f32_e32 v33, v4, v4
	v_max_f32_e32 v34, v20, v20
	v_max_f32_e32 v33, v34, v33
	v_max_f32_e32 v34, v5, v5
	v_max_f32_e32 v35, v21, v21
	v_max_f32_e32 v34, v35, v34
	v_max3_f32 v32, v32, v33, v34
	v_max_f32_e32 v33, v6, v6
	v_max_f32_e32 v34, v22, v22
	v_max_f32_e32 v33, v34, v33
	v_max_f32_e32 v34, v7, v7
	v_max_f32_e32 v35, v23, v23
	v_max_f32_e32 v34, v35, v34
	v_max3_f32 v32, v32, v33, v34
	v_max_f32_e32 v33, v8, v8
	v_max_f32_e32 v34, v24, v24
	v_max_f32_e32 v33, v34, v33
	v_max_f32_e32 v34, v9, v9
	v_max_f32_e32 v35, v25, v25
	v_max_f32_e32 v34, v35, v34
	v_max3_f32 v32, v32, v33, v34
	v_max_f32_e32 v33, v10, v10
	v_max_f32_e32 v34, v26, v26
	v_max_f32_e32 v33, v34, v33
	v_max_f32_e32 v34, v11, v11
	v_max_f32_e32 v35, v27, v27
	v_max_f32_e32 v34, v35, v34
	v_max3_f32 v32, v32, v33, v34
	v_max_f32_e32 v33, v12, v12
	v_max_f32_e32 v34, v28, v28
	v_max_f32_e32 v33, v34, v33
	v_max_f32_e32 v34, v13, v13
	v_max_f32_e32 v35, v29, v29
	v_max_f32_e32 v34, v35, v34
	v_max3_f32 v32, v32, v33, v34
	v_max_f32_e32 v33, v14, v14
	v_max_f32_e32 v34, v30, v30
	v_max_f32_e32 v33, v34, v33
	v_max_f32_e32 v34, v15, v15
	v_max_f32_e32 v35, v31, v31
	v_max_f32_e32 v34, v35, v34
	v_max3_f32 v32, v32, v33, v34
	v_cndmask_b32_e32 v33, v219, v221, vcc
	v_lshlrev_b32_e32 v161, 2, v33
	ds_bpermute_b32 v33, v161, v32
	s_waitcnt lgkmcnt(0)
	v_max_f32_e32 v33, v33, v33
	v_max_f32_e32 v192, v32, v33
	v_sub_f32_e32 v228, 0, v192
	v_sub_f32_e32 v229, 0, v192
	v_sub_f32_e32 v230, 0, v192
	v_sub_f32_e32 v231, 0, v192
	v_sub_f32_e32 v232, 0, v192
	v_sub_f32_e32 v233, 0, v192
	v_sub_f32_e32 v234, 0, v192
	v_sub_f32_e32 v235, 0, v192
	v_sub_f32_e32 v236, 0, v192
	v_sub_f32_e32 v237, 0, v192
	v_sub_f32_e32 v238, 0, v192
	v_sub_f32_e32 v239, 0, v192
	v_sub_f32_e32 v240, 0, v192
	v_sub_f32_e32 v241, 0, v192
	v_sub_f32_e32 v242, 0, v192
	v_sub_f32_e32 v243, 0, v192
	v_sub_f32_e32 v16, v16, v192
	v_sub_f32_e32 v0, v0, v192
	v_exp_f32_e32 v48, v16
	v_sub_f32_e32 v16, v17, v192
	v_exp_f32_e32 v32, v0
	v_sub_f32_e32 v0, v1, v192
	v_exp_f32_e32 v49, v16
	v_sub_f32_e32 v16, v18, v192
	v_exp_f32_e32 v33, v0
	v_sub_f32_e32 v0, v2, v192
	v_exp_f32_e32 v50, v16
	v_sub_f32_e32 v16, v19, v192
	v_exp_f32_e32 v34, v0
	v_sub_f32_e32 v0, v3, v192
	v_exp_f32_e32 v51, v16
	v_sub_f32_e32 v16, v20, v192
	v_exp_f32_e32 v35, v0
	v_sub_f32_e32 v0, v4, v192
	v_exp_f32_e32 v52, v16
	v_sub_f32_e32 v16, v21, v192
	v_exp_f32_e32 v36, v0
	v_sub_f32_e32 v0, v5, v192
	v_exp_f32_e32 v53, v16
	v_sub_f32_e32 v16, v22, v192
	v_exp_f32_e32 v37, v0
	v_sub_f32_e32 v0, v6, v192
	v_exp_f32_e32 v54, v16
	v_sub_f32_e32 v16, v23, v192
	v_exp_f32_e32 v38, v0
	v_sub_f32_e32 v0, v7, v192
	v_exp_f32_e32 v55, v16
	v_sub_f32_e32 v16, v24, v192
	v_exp_f32_e32 v39, v0
	v_sub_f32_e32 v0, v8, v192
	v_exp_f32_e32 v56, v16
	v_sub_f32_e32 v16, v25, v192
	v_exp_f32_e32 v40, v0
	v_sub_f32_e32 v0, v9, v192
	v_exp_f32_e32 v57, v16
	v_sub_f32_e32 v16, v26, v192
	v_exp_f32_e32 v41, v0
	v_sub_f32_e32 v0, v10, v192
	v_exp_f32_e32 v58, v16
	v_sub_f32_e32 v16, v27, v192
	v_exp_f32_e32 v42, v0
	v_sub_f32_e32 v0, v11, v192
	v_exp_f32_e32 v59, v16
	v_sub_f32_e32 v16, v28, v192
	v_exp_f32_e32 v43, v0
	v_sub_f32_e32 v0, v12, v192
	v_exp_f32_e32 v60, v16
	v_sub_f32_e32 v16, v29, v192
	v_exp_f32_e32 v44, v0
	v_sub_f32_e32 v0, v13, v192
	v_exp_f32_e32 v61, v16
	v_sub_f32_e32 v16, v30, v192
	v_exp_f32_e32 v45, v0
	v_sub_f32_e32 v0, v14, v192
	v_exp_f32_e32 v62, v16
	v_sub_f32_e32 v16, v31, v192
	v_exp_f32_e32 v46, v0
	v_sub_f32_e32 v0, v15, v192
	v_exp_f32_e32 v63, v16
	v_exp_f32_e32 v47, v0
	v_lshlrev_b32_e32 v0, 2, v219
	v_and_or_b32 v180, v0, s4, v194
	v_mov_b32_e32 v0, s15
	v_mov_b32_e32 v1, s16
	v_mov_b32_e32 v2, s12
	v_mov_b32_e32 v3, s14
	v_mov_b32_e32 v194, 0
	v_or_b32_e32 v181, 4, v180
	v_or_b32_e32 v182, 8, v180
	v_or_b32_e32 v183, 12, v180
	v_or_b32_e32 v184, 32, v180
	v_or_b32_e32 v185, 36, v180
	v_or_b32_e32 v186, 40, v180
	v_or_b32_e32 v165, 44, v180
	v_or_b32_e32 v187, 64, v180
	v_or_b32_e32 v177, 0x44, v180
	v_or_b32_e32 v188, 0x48, v180
	v_or_b32_e32 v178, 0x4c, v180
	v_or_b32_e32 v189, 0x60, v180
	v_or_b32_e32 v179, 0x64, v180
	v_or_b32_e32 v190, 0x68, v180
	v_or_b32_e32 v191, 0x6c, v180
	v_cndmask_b32_e64 v171, v0, v1, s[42:43]
	v_cndmask_b32_e64 v170, v2, v3, s[42:43]
	v_cndmask_b32_e64 v169, v0, v1, s[44:45]
	v_cndmask_b32_e64 v168, v2, v3, s[44:45]
	s_mov_b32 s15, 1
	s_mov_b32 s12, 3
	s_mov_b32 s14, 1
	v_mov_b32_e32 v0, 0
	v_mov_b32_e32 v1, v194
	v_mov_b32_e32 v2, v194
	v_mov_b32_e32 v3, v194
	v_mov_b32_e32 v4, v194
	v_mov_b32_e32 v5, v194
	v_mov_b32_e32 v6, v194
	v_mov_b32_e32 v7, v194
	v_mov_b32_e32 v8, v194
	v_mov_b32_e32 v9, v194
	v_mov_b32_e32 v10, v194
	v_mov_b32_e32 v11, v194
	v_mov_b32_e32 v12, v194
	v_mov_b32_e32 v13, v194
	v_mov_b32_e32 v14, v194
	v_mov_b32_e32 v15, v194
	v_mov_b32_e32 v16, 0
	v_mov_b32_e32 v17, v194
	v_mov_b32_e32 v18, v194
	v_mov_b32_e32 v19, v194
	v_mov_b32_e32 v20, v194
	v_mov_b32_e32 v21, v194
	v_mov_b32_e32 v22, v194
	v_mov_b32_e32 v23, v194
	v_mov_b32_e32 v24, v194
	v_mov_b32_e32 v25, v194
	v_mov_b32_e32 v26, v194
	v_mov_b32_e32 v27, v194
	v_mov_b32_e32 v28, v194
	v_mov_b32_e32 v29, v194
	v_mov_b32_e32 v30, v194
	v_mov_b32_e32 v31, v194

; #define WAIT_BAR(N) asm volatile("s_waitcnt vmcnt(" #N ") lgkmcnt(0)\n\ts_barrier" ::: "memory")
; __device__ __forceinline__ int pi_row(int i) { return (i & ~12) | ((i & 4) << 1) | ((i & 8) >> 1); }
; #define D_ISSUE() do { D_ISSUE_A(); D_ISSUE_B(); } while (0)
; __device__ __forceinline__ void attn_diff_unit(LAS unsigned char* lds, const bf16_t* __restrict__ Q, const bf16_t* __restrict__ Kb, const bf16_t* __restrict__ VT, bf16_t* O,
;                                                int qrow0, int b, int h, int ntiles, float lam, const float* subln_g) {
;     ...
;     const bf16_t* kbase = Kb + (size_t)b * KVLEN * D + h * 128; const bf16_t* vbase = VT + (size_t)(b * 1024 + h * 128) * KVLEN;
;     int poff[5], pdst[5]; const bool w0 = (wid == 0);
; #pragma unroll
;     for (int j = 0; j < 5; ++j) { int P = wid + 8 * j; if (P >= 35) P -= 8;
;         const bool isk = (j < 2) || (j == 2 && w0);
;         const int pk = isk ? P : P - 17, g = pk * 64 + lane;
;         const int ik = g / 17, cik = g - ik * 17, iv = g / 9, civ = g - iv * 9;
;         poff[j] = isk ? pi_row(ik) * D + (cik > 15 ? 15 : cik) * 8 : iv * KVLEN + (civ > 7 ? 7 : civ) * 8; pdst[j] = pk * 1024; }
;     int ks3 = 0, vs4 = 0;
;     int tiss = 0;
;     ...
;     const int koff = r32 * DK_STRIDE + (sub * 64 + hi * 8) * 2;
;     const int voff = D_VRING + r32 * DV_STRIDE + hi * 16;
;     D_ISSUE(); D_ISSUE();
;     f32x16 o[4];
; #pragma unroll
;     for (int k = 0; k < 4; ++k)
; #pragma unroll
;         for (int r = 0; r < 16; ++r) o[k][r] = 0.f;
;     float mhat = 0.f, lrun = 0.f, fsc = 1.f;
;     f32x16 pA0, pA1, pB0, pB1; bf16x8 pf[4], vf[8];
;     WAIT_BAR(5);
.LBB0_1097:
	s_mul_i32 s14, s2, 0x880000
	v_readlane_b32 s4, v254, 6
	s_mul_hi_i32 s11, s2, 0x880000
	v_readlane_b32 s5, v254, 7
	s_add_u32 s39, s4, s14
	s_addc_u32 s40, s5, s11
	s_lshl_b32 s2, s2, 10
	s_or_b32 s2, s33, s2
	s_mul_hi_i32 s41, s2, 0x2200
	s_mul_i32 s46, s2, 0x2200
	s_add_i32 s2, s12, -8
	s_cmp_gt_i32 s12, 34
	s_cselect_b32 s11, s2, s12
	v_lshl_or_b32 v0, s11, 6, v229
	s_mov_b32 s4, 0x78787879
	v_mul_hi_i32 v1, v0, s4
	v_lshrrev_b32_e32 v3, 31, v1
	v_ashrrev_i32_e32 v1, 3, v1
	v_add_u32_e32 v3, v1, v3
	s_movk_i32 s5, 0xffef
	v_mad_u64_u32 v[0:1], s[34:35], v3, s5, v[0:1]
	v_and_b32_e32 v1, 0x3ffff3, v3
	v_lshlrev_b32_e32 v4, 1, v3
	v_lshrrev_b32_e32 v3, 1, v3
	s_lshl_b32 s14, s11, 10
	s_add_i32 s11, s12, 8
	v_and_b32_e32 v4, 8, v4
	v_and_b32_e32 v3, 4, v3
	v_min_i32_e32 v0, 15, v0
	s_cmp_gt_i32 s12, 26
	v_or3_b32 v1, v1, v4, v3
	v_lshlrev_b32_e32 v0, 3, v0
	s_cselect_b32 s11, s12, s11
	v_lshl_add_u32 v212, v1, 10, v0
	v_lshl_or_b32 v0, s11, 6, v229
	v_mul_hi_i32 v1, v0, s4
	v_lshrrev_b32_e32 v3, 31, v1
	v_ashrrev_i32_e32 v1, 3, v1
	v_add_u32_e32 v3, v1, v3
	v_mad_u64_u32 v[0:1], s[34:35], v3, s5, v[0:1]
	s_lshl_b32 s16, s11, 10
	s_lshl_b32 s3, s3, 10
	v_and_b32_e32 v1, 0x3ffff3, v3
	v_lshlrev_b32_e32 v4, 1, v3
	v_lshrrev_b32_e32 v3, 1, v3
	s_cmp_gt_i32 s12, 10
	v_and_b32_e32 v4, 8, v4
	v_and_b32_e32 v3, 4, v3
	v_min_i32_e32 v0, 15, v0
	s_cselect_b32 s11, 16, 24
	s_sub_i32 s44, s12, 17
	v_or3_b32 v1, v1, v4, v3
	v_lshlrev_b32_e32 v0, 3, v0
	s_add_i32 s11, s44, s11
	v_lshl_add_u32 v214, v1, 10, v0
	v_lshl_or_b32 v0, s11, 6, v229
	s_mov_b32 s5, 0x38e38e39
	v_mul_hi_i32 v1, v0, s5
	v_lshrrev_b32_e32 v3, 31, v1
	v_ashrrev_i32_e32 v1, 1, v1
	s_lshl_b32 s11, s11, 10
	v_add_u32_e32 v3, v1, v3
	s_cmp_gt_i32 s12, 2
	v_mad_u64_u32 v[0:1], s[34:35], v3, -9, v[0:1]
	s_movk_i32 s4, 0x1100
	s_cselect_b32 s12, 24, 32
	v_mul_lo_u32 v1, v3, s4
	v_min_i32_e32 v0, 7, v0
	s_add_i32 s44, s44, s12
	v_lshl_add_u32 v208, v0, 3, v1
	v_lshl_or_b32 v0, s44, 6, v229
	v_mul_hi_i32 v1, v0, s5
	v_lshrrev_b32_e32 v3, 31, v1
	v_ashrrev_i32_e32 v1, 1, v1
	v_add_u32_e32 v3, v1, v3
	s_lshl_b32 s12, s44, 10
	s_lshl_b32 s33, s33, 1
	v_mad_u64_u32 v[0:1], s[34:35], v3, -9, v[0:1]
	s_add_u32 s44, s39, s33
	v_min_i32_e32 v0, 7, v0
	v_mul_lo_u32 v1, v3, s4
	s_addc_u32 s45, s40, 0
	v_readlane_b32 s4, v254, 8
	v_ashrrev_i32_e32 v213, 31, v212
	v_lshlrev_b32_e32 v2, 3, v230
	v_lshl_add_u32 v210, v0, 3, v1
	v_readlane_b32 s5, v254, 9
	s_add_u32 s34, s4, s46
	v_lshlrev_b64 v[0:1], 1, v[212:213]
	s_addc_u32 s35, s5, s41
	v_or_b32_e32 v12, s38, v2
	v_lshl_add_u64 v[2:3], s[44:45], 0, v[0:1]
	s_add_i32 s33, s14, 0
	v_ashrrev_i32_e32 v215, 31, v214
	s_mov_b32 s38, m0
	s_mov_b32 m0, s33
	s_nop 0
	global_load_lds_dwordx4 v[2:3], off
	s_mov_b32 m0, s38
	v_lshlrev_b64 v[2:3], 1, v[214:215]
	s_add_i32 s33, s16, 0
	v_lshl_add_u64 v[4:5], s[44:45], 0, v[2:3]
	s_mov_b32 s38, m0
	s_mov_b32 m0, s33
	s_nop 0
	global_load_lds_dwordx4 v[4:5], off
	s_mov_b32 m0, s38
	s_and_b64 s[38:39], s[42:43], exec
	v_ashrrev_i32_e32 v207, 31, v206
	s_cselect_b32 s39, s45, s35
	s_cselect_b32 s38, s44, s34
	v_lshlrev_b64 v[4:5], 1, v[206:207]
	v_lshl_add_u64 v[6:7], s[38:39], 0, v[4:5]
	s_add_i32 s29, s29, s3
	v_ashrrev_i32_e32 v209, 31, v208
	v_readlane_b32 s4, v255, 5
	s_mov_b32 s33, m0
	s_mov_b32 m0, s29
	s_nop 0
	global_load_lds_dwordx4 v[6:7], off
	s_mov_b32 m0, s33
	v_lshlrev_b64 v[6:7], 1, v[208:209]
	s_add_i32 s29, s11, s4
	v_lshl_add_u64 v[8:9], s[34:35], 0, v[6:7]
	s_mov_b32 s33, m0
	s_mov_b32 m0, s29
	s_nop 0
	global_load_lds_dwordx4 v[8:9], off
	s_mov_b32 m0, s33
	v_ashrrev_i32_e32 v211, 31, v210
	s_add_i32 s29, s12, s4
	v_lshlrev_b64 v[8:9], 1, v[210:211]
	s_add_u32 s38, s44, 0x20000
	v_lshl_add_u64 v[10:11], s[34:35], 0, v[8:9]
	s_mov_b32 s33, m0
	s_mov_b32 m0, s29
	s_nop 0
	global_load_lds_dwordx4 v[10:11], off
	s_mov_b32 m0, s33
	s_addc_u32 s39, s45, 0
	s_add_i32 s29, 0, 0x4400
	v_lshl_add_u64 v[10:11], s[38:39], 0, v[0:1]
	s_add_i32 s33, s14, s29
	s_mov_b32 s40, m0
	s_mov_b32 m0, s33
	s_nop 0
	global_load_lds_dwordx4 v[10:11], off
	s_mov_b32 m0, s40
	s_add_i32 s29, s16, s29
	s_add_u32 s40, s34, 0x80
	s_addc_u32 s41, s35, 0
	s_and_b64 s[46:47], s[42:43], exec
	v_lshl_add_u64 v[10:11], s[38:39], 0, v[2:3]
	s_mov_b32 s33, m0
	s_mov_b32 m0, s29
	s_nop 0
	global_load_lds_dwordx4 v[10:11], off
	s_mov_b32 m0, s33
	s_cselect_b32 s39, s39, s41
	s_cselect_b32 s38, s38, s40
	s_add_i32 s17, s17, s3
	v_readlane_b32 s4, v255, 6
	v_lshl_add_u64 v[10:11], s[38:39], 0, v[4:5]
	s_mov_b32 s29, m0
	s_mov_b32 m0, s17
	s_nop 0
	global_load_lds_dwordx4 v[10:11], off
	s_mov_b32 m0, s29
	s_add_i32 s17, s11, s4
	v_lshl_add_u64 v[10:11], s[40:41], 0, v[6:7]
	s_mov_b32 s29, m0
	s_mov_b32 m0, s17
	s_nop 0
	global_load_lds_dwordx4 v[10:11], off
	s_mov_b32 m0, s29
	s_add_i32 s17, s12, s4
	s_add_u32 s38, s44, 0x40000
	v_lshl_add_u64 v[10:11], s[40:41], 0, v[8:9]
	s_mov_b32 s29, m0
	s_mov_b32 m0, s17
	s_nop 0
	global_load_lds_dwordx4 v[10:11], off
	s_mov_b32 m0, s29
	s_addc_u32 s39, s45, 0
	s_add_i32 s17, 0, 0x8800
	s_add_i32 s29, s14, s17
	s_add_i32 s17, s16, s17
	s_add_u32 s40, s34, 0x100
	s_waitcnt vmcnt(5) lgkmcnt(0)
	s_barrier
; #define LAS __attribute__((address_space(3)))
; #define MFMA32(a, b, c) __builtin_amdgcn_mfma_f32_32x32x16_bf16((a), (b), (c), 0, 0, 0)
; #define WAIT_BAR(N) asm volatile("s_waitcnt vmcnt(" #N ") lgkmcnt(0)\n\ts_barrier" ::: "memory")
; #define D_ISSUE() do { D_ISSUE_A(); D_ISSUE_B(); } while (0)
; template <int NKD, int KSTRIDE> __device__ __forceinline__ void att_qk(const LAS unsigned char* kb, const bf16x8 (&qr)[NKD], f32x16& c0, f32x16& c1) {
;     f32x16 z;
; #pragma unroll
;     for (int r = 0; r < 16; ++r) z[r] = 0.f;
; #pragma unroll
;     for (int d0 = 0; d0 < NKD; ++d0) { const bf16x8 k0 = *(const LAS bf16x8*)(kb + d0 * 32), k1 = *(const LAS bf16x8*)(kb + 32 * KSTRIDE + d0 * 32);
;         c0 = MFMA32(k0, qr[d0], d0 == 0 ? z : c0); c1 = MFMA32(k1, qr[d0], d0 == 0 ? z : c1); }
; __device__ __forceinline__ void attn_diff_unit(LAS unsigned char* lds, const bf16_t* __restrict__ Q, const bf16_t* __restrict__ Kb, const bf16_t* __restrict__ VT, bf16_t* O,
;                                                int qrow0, int b, int h, int ntiles, float lam, const float* subln_g) {
;     ...
;     D_ISSUE();
;     att_qk<4, DK_STRIDE>(lds + koff, qr, pA0, pA1);
;     att_first(pA0, pA1, mhat);
;     WAIT_BAR(5);
	s_addc_u32 s41, s35, 0
	v_lshl_add_u64 v[0:1], s[38:39], 0, v[0:1]
	s_mov_b32 s33, m0
	s_mov_b32 m0, s29
	s_nop 0
	global_load_lds_dwordx4 v[0:1], off
	s_mov_b32 m0, s33
	s_and_b64 s[46:47], s[42:43], exec
	v_lshl_add_u64 v[0:1], s[38:39], 0, v[2:3]
	s_mov_b32 s29, m0
	s_mov_b32 m0, s17
	s_nop 0
	global_load_lds_dwordx4 v[0:1], off
	s_mov_b32 m0, s29
	s_cselect_b32 s39, s39, s41
	s_cselect_b32 s38, s38, s40
	v_mul_u32_u24_e32 v10, 0x110, v228
	v_lshl_add_u64 v[0:1], s[38:39], 0, v[4:5]
	s_add_i32 s13, s13, s3
	s_mov_b32 s17, m0
	s_mov_b32 m0, s13
	s_nop 0
	global_load_lds_dwordx4 v[0:1], off
	s_mov_b32 m0, s17
	v_readlane_b32 s4, v255, 7
	v_lshl_add_u32 v248, v12, 1, v10
	v_lshl_add_u64 v[0:1], s[40:41], 0, v[6:7]
	s_add_i32 s13, s11, s4
	s_mov_b32 s17, m0
	s_mov_b32 m0, s13
	s_nop 0
	global_load_lds_dwordx4 v[0:1], off
	s_mov_b32 m0, s17
	v_lshl_add_u64 v[0:1], s[40:41], 0, v[8:9]
	s_add_i32 s13, s12, s4
	s_mov_b32 s17, m0
	s_mov_b32 m0, s13
	s_nop 0
	global_load_lds_dwordx4 v[0:1], off
	s_mov_b32 m0, s17
	v_add_u32_e32 v249, 0, v248
	ds_read_b128 v[16:19], v249 offset:8704
	ds_read_b128 v[20:23], v249
	ds_read_b128 v[48:51], v249 offset:32
	ds_read_b128 v[52:55], v249 offset:8736
	s_waitcnt lgkmcnt(2)
	v_mfma_f32_32x32x16_bf16 v[32:47], v[20:23], v[142:145], 0
	v_cmp_lt_i32_e32 vcc, v221, v220
	s_mov_b32 s80, 0
	s_mov_b32 s81, s80
	s_mov_b32 s82, s80
	s_mov_b32 s83, s80
	s_mov_b32 s84, s80
	s_mov_b32 s85, s80
	v_mfma_f32_32x32x16_bf16 v[16:31], v[16:19], v[142:145], 0
	s_mov_b32 s86, s80
	s_mov_b32 s87, s80
	s_mov_b32 s88, s80
	s_mov_b32 s89, s80
	s_mov_b32 s90, s80
	s_mov_b32 s91, s80
	s_mov_b32 s92, s80
	s_waitcnt lgkmcnt(1)
	v_mfma_f32_32x32x16_bf16 v[32:47], v[48:51], v[138:141], v[32:47]
	s_mov_b32 s93, s80
	s_mov_b32 s94, s80
	s_mov_b32 s95, s80
	v_mov_b64_e32 v[0:1], s[80:81]
	s_movk_i32 s4, 0x90
	v_mov_b64_e32 v[14:15], s[94:95]
	v_mad_u32_u24 v232, v228, s4, v194
	s_waitcnt lgkmcnt(0)
	v_mfma_f32_32x32x16_bf16 v[16:31], v[52:55], v[138:141], v[16:31]
	ds_read_b128 v[48:51], v249 offset:64
	ds_read_b128 v[52:55], v249 offset:8768
	s_cmpk_lt_u32 s8, 0x100
	s_movk_i32 s4, 0x100
	v_mov_b64_e32 v[2:3], s[82:83]
	v_mov_b64_e32 v[4:5], s[84:85]
	v_mov_b64_e32 v[6:7], s[86:87]
	v_mov_b64_e32 v[8:9], s[88:89]
	s_waitcnt lgkmcnt(1)
	v_mfma_f32_32x32x16_bf16 v[32:47], v[48:51], v[134:137], v[32:47]
	v_mov_b64_e32 v[10:11], s[90:91]
	v_mov_b64_e32 v[12:13], s[92:93]
	s_cselect_b64 s[48:49], -1, 0
	s_cmpk_gt_u32 s8, 0xff
	s_mov_b32 s2, 3
	s_mov_b32 s28, 1
	v_add_u32_e32 v200, 0, v232
	s_waitcnt lgkmcnt(0)
	v_mfma_f32_32x32x16_bf16 v[16:31], v[52:55], v[134:137], v[16:31]
	ds_read_b128 v[48:51], v249 offset:96
	ds_read_b128 v[52:55], v249 offset:8800
	s_waitcnt vmcnt(5) lgkmcnt(0)
	s_barrier
; #define WAIT_BAR(N) asm volatile("s_waitcnt vmcnt(" #N ") lgkmcnt(0)\n\ts_barrier" ::: "memory")
; __device__ __forceinline__ void att_first(f32x16& c0, f32x16& c1, float& mhat) {
;     float rm = fmaxf(c0[0], c1[0]);
; #pragma unroll
;     for (int r = 1; r < 16; ++r) rm = fmaxf(rm, fmaxf(c0[r], c1[r]));
;     rm = fmaxf(rm, __shfl_xor(rm, 32)); mhat = rm;
; #pragma unroll
;     for (int r = 0; r < 16; ++r) { c0[r] = __builtin_amdgcn_exp2f(c0[r] - mhat); c1[r] = __builtin_amdgcn_exp2f(c1[r] - mhat); }
; }
; __device__ __forceinline__ void attn_diff_unit(LAS unsigned char* lds, const bf16_t* __restrict__ Q, const bf16_t* __restrict__ Kb, const bf16_t* __restrict__ VT, bf16_t* O,
;                                                int qrow0, int b, int h, int ntiles, float lam, const float* subln_g) {
;     ...
;     att_qk<4, DK_STRIDE>(lds + koff, qr, pA0, pA1);
;     att_first(pA0, pA1, mhat);
;     WAIT_BAR(5);
;     int kc = 1, vc = 0;
	s_cselect_b64 s[52:53], -1, 0
	v_mov_b32_e32 v201, 0
	s_mov_b32 s46, 3
	s_mov_b32 s13, s80
	s_mov_b32 s17, 1
	s_waitcnt lgkmcnt(1)
	v_mfma_f32_32x32x16_bf16 v[32:47], v[48:51], v[130:133], v[32:47]
	v_readlane_b32 s84, v255, 12
	s_waitcnt lgkmcnt(0)
	v_mfma_f32_32x32x16_bf16 v[16:31], v[52:55], v[130:133], v[16:31]
	s_nop 8
	v_max_f32_e32 v49, v33, v33
	v_max_f32_e32 v50, v34, v34
	v_max_f32_e32 v51, v35, v35
	v_max_f32_e32 v48, v17, v17
	v_max_f32_e32 v48, v49, v48
	v_max_f32_e32 v49, v18, v18
	v_max_f32_e32 v49, v50, v49
	v_max_f32_e32 v50, v19, v19
	v_max3_f32 v48, v32, v16, v48
	v_max_f32_e32 v50, v51, v50
	v_max3_f32 v48, v48, v49, v50
	v_max_f32_e32 v49, v20, v20
	v_max_f32_e32 v50, v36, v36
	v_max_f32_e32 v49, v50, v49
	v_max_f32_e32 v50, v21, v21
	v_max_f32_e32 v51, v37, v37
	v_max_f32_e32 v50, v51, v50
	v_max3_f32 v48, v48, v49, v50
	v_max_f32_e32 v49, v22, v22
	v_max_f32_e32 v50, v38, v38
	v_max_f32_e32 v49, v50, v49
	v_max_f32_e32 v50, v23, v23
	v_max_f32_e32 v51, v39, v39
	v_max_f32_e32 v50, v51, v50
	v_max3_f32 v48, v48, v49, v50
	v_max_f32_e32 v49, v24, v24
	v_max_f32_e32 v50, v40, v40
	v_max_f32_e32 v49, v50, v49
	v_max_f32_e32 v50, v25, v25
	v_max_f32_e32 v51, v41, v41
	v_max_f32_e32 v50, v51, v50
	v_max3_f32 v48, v48, v49, v50
	v_max_f32_e32 v49, v26, v26
	v_max_f32_e32 v50, v42, v42
	v_max_f32_e32 v49, v50, v49
	v_max_f32_e32 v50, v27, v27
	v_max_f32_e32 v51, v43, v43
	v_max_f32_e32 v50, v51, v50
	v_max3_f32 v48, v48, v49, v50
	v_max_f32_e32 v49, v28, v28
	v_max_f32_e32 v50, v44, v44
	v_max_f32_e32 v49, v50, v49
	v_max_f32_e32 v50, v29, v29
	v_max_f32_e32 v51, v45, v45
	v_max_f32_e32 v50, v51, v50
	v_max3_f32 v48, v48, v49, v50
	v_max_f32_e32 v49, v30, v30
	v_max_f32_e32 v50, v46, v46
	v_max_f32_e32 v49, v50, v49
	v_max_f32_e32 v50, v31, v31
	v_max_f32_e32 v51, v47, v47
	v_max_f32_e32 v50, v51, v50
	v_max3_f32 v48, v48, v49, v50
	v_cndmask_b32_e32 v49, v219, v221, vcc
	v_lshlrev_b32_e32 v231, 2, v49
	ds_bpermute_b32 v49, v231, v48
	s_waitcnt lgkmcnt(0)
	v_max_f32_e32 v49, v49, v49
	v_max_f32_e32 v250, v48, v49
	v_sub_f32_e32 v32, v32, v250
	v_sub_f32_e32 v16, v16, v250
	v_exp_f32_e32 v80, v32
	v_sub_f32_e32 v32, v33, v250
	v_exp_f32_e32 v64, v16
	v_sub_f32_e32 v16, v17, v250
	v_exp_f32_e32 v81, v32
	v_sub_f32_e32 v32, v34, v250
	v_exp_f32_e32 v65, v16
	v_sub_f32_e32 v16, v18, v250
	v_exp_f32_e32 v82, v32
	v_sub_f32_e32 v32, v35, v250
	v_exp_f32_e32 v66, v16
	v_sub_f32_e32 v16, v19, v250
	v_exp_f32_e32 v83, v32
	v_sub_f32_e32 v32, v36, v250
	v_exp_f32_e32 v67, v16
	v_sub_f32_e32 v16, v20, v250
	v_exp_f32_e32 v84, v32
	v_sub_f32_e32 v32, v37, v250
	v_exp_f32_e32 v68, v16
	v_sub_f32_e32 v16, v21, v250
	v_exp_f32_e32 v85, v32
	v_sub_f32_e32 v32, v38, v250
	v_exp_f32_e32 v69, v16
	v_sub_f32_e32 v16, v22, v250
	v_exp_f32_e32 v86, v32
	v_sub_f32_e32 v32, v39, v250
	v_exp_f32_e32 v70, v16
	v_sub_f32_e32 v16, v23, v250
	v_exp_f32_e32 v87, v32
	v_sub_f32_e32 v32, v40, v250
	v_exp_f32_e32 v71, v16
	v_sub_f32_e32 v16, v24, v250
	v_exp_f32_e32 v88, v32
	v_sub_f32_e32 v32, v41, v250
	v_exp_f32_e32 v72, v16
	v_sub_f32_e32 v16, v25, v250
	v_exp_f32_e32 v89, v32
	v_sub_f32_e32 v32, v42, v250
	v_exp_f32_e32 v73, v16
	v_sub_f32_e32 v16, v26, v250
	v_exp_f32_e32 v90, v32
	v_sub_f32_e32 v32, v43, v250
	v_exp_f32_e32 v74, v16
	v_sub_f32_e32 v16, v27, v250
	v_exp_f32_e32 v91, v32
	v_sub_f32_e32 v32, v44, v250
	v_exp_f32_e32 v75, v16
	v_sub_f32_e32 v16, v28, v250
	v_exp_f32_e32 v92, v32
	v_sub_f32_e32 v32, v45, v250
	v_exp_f32_e32 v76, v16
	v_sub_f32_e32 v16, v29, v250
	v_exp_f32_e32 v93, v32
	v_sub_f32_e32 v32, v46, v250
	v_exp_f32_e32 v77, v16
	v_sub_f32_e32 v16, v30, v250
	v_exp_f32_e32 v94, v32
	v_sub_f32_e32 v32, v47, v250
	v_exp_f32_e32 v78, v16
	v_sub_f32_e32 v16, v31, v250
	v_exp_f32_e32 v95, v32
	v_exp_f32_e32 v79, v16
	v_lshlrev_b32_e32 v16, 2, v219
	v_and_or_b32 v236, v16, s4, v194
	v_mov_b64_e32 v[62:63], v[14:15]
	v_mov_b64_e32 v[30:31], v[14:15]
	v_mov_b64_e32 v[46:47], v[14:15]
	v_or_b32_e32 v237, 4, v236
	v_or_b32_e32 v238, 8, v236
	v_or_b32_e32 v239, 12, v236
	v_or_b32_e32 v240, 32, v236
	v_or_b32_e32 v241, 36, v236
	v_or_b32_e32 v242, 40, v236
	v_or_b32_e32 v194, 44, v236
	v_or_b32_e32 v243, 64, v236
	v_or_b32_e32 v233, 0x44, v236
	v_or_b32_e32 v244, 0x48, v236
	v_or_b32_e32 v234, 0x4c, v236
	v_or_b32_e32 v245, 0x60, v236
	v_or_b32_e32 v235, 0x64, v236
	v_or_b32_e32 v246, 0x68, v236
	v_or_b32_e32 v247, 0x6c, v236
	v_mov_b64_e32 v[60:61], v[12:13]
	v_mov_b64_e32 v[58:59], v[10:11]
	v_mov_b64_e32 v[56:57], v[8:9]
	v_mov_b64_e32 v[54:55], v[6:7]
	v_mov_b64_e32 v[52:53], v[4:5]
	v_mov_b64_e32 v[50:51], v[2:3]
	v_mov_b64_e32 v[48:49], v[0:1]
	v_mov_b64_e32 v[28:29], v[12:13]
	v_mov_b64_e32 v[26:27], v[10:11]
	v_mov_b64_e32 v[24:25], v[8:9]
	v_mov_b64_e32 v[22:23], v[6:7]
	v_mov_b64_e32 v[20:21], v[4:5]
	v_mov_b64_e32 v[18:19], v[2:3]
	v_mov_b64_e32 v[16:17], v[0:1]
	v_mov_b64_e32 v[44:45], v[12:13]
	v_mov_b64_e32 v[42:43], v[10:11]
	v_mov_b64_e32 v[40:41], v[8:9]
	v_mov_b64_e32 v[38:39], v[6:7]
	v_mov_b64_e32 v[36:37], v[4:5]
	v_mov_b64_e32 v[34:35], v[2:3]
	v_mov_b64_e32 v[32:33], v[0:1]
